# attention: the second kv-head body's q / rope-q lines touched (L2 prefetch into a dead register) from the first body
# baseline (speedup 1.0000x reference)
; #define LAS __attribute__((address_space(3)))
; #define MFMA32(a, b, c) __builtin_amdgcn_mfma_f32_32x32x16_bf16((a), (b), (c), 0, 0, 0)
; __device__ __forceinline__ void phase4_attn(const Args& a, LAS unsigned char* lds) {
;     ...
;                 const int bh = b * 2 + hkv, head = hkv * 4 + g;
;                 int tid = tid0; asm volatile("" : "+v"(tid));
;                 const int lane = tid & 63, r = lane & 31, h = lane >> 5, ql = 32 * half + r, pos = 64 * t + ql, tok = b * 2048 + pos;
;                 comb[hkv][0] = zero16(); comb[hkv][1] = zero16();
;                 const float g0 = gates[(size_t)tok * 24 + head * 3 + 0], g1 = gates[(size_t)tok * 24 + head * 3 + 1], g2 = gates[(size_t)tok * 24 + head * 3 + 2];
;                 __syncthreads();
;                 {
;                     const bf16_t* kc = kcmp + (size_t)bh * 128 * 64; const bf16_t* vc = vcmpT + (size_t)bh * 64 * 128;
; #pragma unroll
;                     for (int i = 0; i < 2; ++i) { const int c = tid + 512 * i;
;                         const u32x4 kv = *(const u32x4*)(kc + (size_t)c * 8);
;                         *(LAS u32x4*)(lds + A_CMPK + (c >> 3) * A_KSTR + (c & 7) * 16) = kv;
;                         const u32x4 vv = *(const u32x4*)(vc + (size_t)c * 8);
;                         LAS unsigned char* vp = lds + A_CMPV + (c >> 4) * A_CVSTR + (c & 15) * 16;
;                         *(LAS u32x2*)vp = (u32x2){vv.x, vv.y}; *(LAS u32x2*)(vp + 8) = (u32x2){vv.z, vv.w}; }
;                 }
;                 bf16x8_t qf[4];
; #pragma unroll
;                 for (int ks = 0; ks < 4; ++ks) qf[ks] = __builtin_nontemporal_load((const bf16x8_t*)(qn + (size_t)tok * 512 + head * 64 + 16 * ks + 8 * h));
;                 __syncthreads();
;                 {
;                     f32x16 s4[4];
; #pragma unroll
;                     for (int mt = 0; mt < 4; ++mt) { s4[mt] = zero16();
; #pragma unroll
;                         for (int ks = 0; ks < 4; ++ks) { const bf16x8_t ka = *(const LAS bf16x8_t*)(lds + A_CMPK + (32 * mt + r) * A_KSTR + 32 * ks + 16 * h); s4[mt] = MFMA32(ka, qf[ks], s4[mt]); } }
.LBB0_715:
	s_and_b64 s[0:1], s[64:65], exec
	v_readlane_b32 s0, v254, 29
	v_readlane_b32 s1, v254, 30
	v_mov_b32_e32 v152, v184
	s_cselect_b32 s38, s0, s1
	s_lshl_b32 s24, s38, 6
	s_waitcnt vmcnt(0)
	v_and_b32_e32 v100, 31, v152
	v_or_b32_e32 v98, s79, v100
	v_or_b32_e32 v154, s24, v98
	v_or_b32_e32 v4, s39, v154
	v_mad_i64_i32 v[0:1], s[4:5], v4, s83, v[116:117]
	global_load_dwordx3 v[112:114], v[0:1], off
	v_lshlrev_b32_e32 v0, 4, v152
	v_ashrrev_i32_e32 v153, 31, v152
	v_readlane_b32 s6, v254, 39
	v_and_b32_e32 v1, 0x70, v0
	v_and_b32_e32 v0, 0xf0, v0
	v_lshlrev_b64 v[10:11], 4, v[152:153]
	v_readlane_b32 s7, v254, 40
	v_add_u32_e32 v6, s85, v1
	v_add_u32_e32 v8, s86, v0
	v_lshl_add_u64 v[0:1], s[6:7], 0, v[10:11]
	s_waitcnt lgkmcnt(0)
	s_barrier
	v_readlane_b32 s8, v254, 31
	v_readlane_b32 s9, v254, 32
	global_load_dwordx4 v[16:19], v[0:1], off
	v_add_u32_e32 v14, 0x200, v152
	v_ashrrev_i32_e32 v15, 31, v14
	v_lshlrev_b64 v[12:13], 4, v[14:15]
	v_lshl_add_u64 v[36:37], s[8:9], 0, v[10:11]
	global_load_dwordx4 v[20:23], v[36:37], off
	v_lshl_add_u64 v[36:37], s[6:7], 0, v[12:13]
	global_load_dwordx4 v[24:27], v[36:37], off
	v_lshl_add_u64 v[36:37], s[8:9], 0, v[12:13]
	global_load_dwordx4 v[28:31], v[36:37], off
	v_readlane_b32 s4, v254, 24
	v_readlane_b32 s5, v254, 25
	v_ashrrev_i32_e32 v5, 31, v4
	v_bfe_u32 v101, v152, 5, 1
	v_lshlrev_b64 v[72:73], 10, v[4:5]
	v_lshlrev_b32_e32 v118, 4, v101
	v_lshl_add_u64 v[0:1], s[4:5], 0, v[72:73]
	v_lshl_add_u64 v[4:5], v[0:1], 0, v[118:119]
	global_load_dwordx4 v[0:3], v[4:5], off nt
	global_load_dwordx4 v[74:77], v[4:5], off offset:32 nt
	global_load_dwordx4 v[68:71], v[4:5], off offset:64 nt
	global_load_dwordx4 v[64:67], v[4:5], off offset:96 nt
	global_load_dword v159, v[4:5], off offset:512
	v_ashrrev_i32_e32 v99, 3, v152
	v_ashrrev_i32_e32 v7, 4, v152
	v_mul_u32_u24_e32 v153, 0x90, v100
	v_add3_u32 v82, s85, v118, v153
	v_mad_u32_u24 v32, v99, s87, v6
	v_mad_u32_u24 v33, v7, s94, v8
	v_add_u32_e32 v35, 0x2100, v33
	s_cmp_gt_u32 s38, 15
	s_cselect_b64 s[0:1], -1, 0
	s_cmp_lt_u32 s38, 16
	s_mov_b64 s[2:3], -1
	s_cselect_b64 s[62:63], -1, 0
	s_waitcnt vmcnt(8)
	ds_write_b128 v32, v[16:19]
	s_waitcnt vmcnt(7)
	ds_write2_b64 v33, v[20:21], v[22:23] offset1:1
	s_waitcnt vmcnt(6)
	ds_write_b128 v32, v[24:27] offset:9216
	s_waitcnt vmcnt(5)
	ds_write2_b64 v35, v[28:29], v[30:31] offset1:1
	s_waitcnt lgkmcnt(0)
	s_barrier
	s_waitcnt vmcnt(0)
	v_mov_b32_e32 v84, v0
	v_mov_b32_e32 v85, v1
	v_mov_b32_e32 v86, v2
	v_mov_b32_e32 v87, v3
	v_lshlrev_b32_e32 v155, 2, v101
	v_lshlrev_b32_e32 v156, 3, v101
	v_mul_u32_u24_e32 v157, 0x108, v100
	v_add3_u32 v244, s86, v156, v157
	v_add_u32_e32 v245, 0x2000, v244
	v_lshlrev_b32_e32 v239, 4, v155
	v_sub_u32_e32 v236, v154, v239
	v_subrev_u32_e32 v236, 31, v236
	v_ashrrev_i32_e32 v236, 4, v236
	v_cmp_lt_i32_e32 vcc, v185, v188
	s_nop 1
	v_cndmask_b32_e32 v239, v115, v185, vcc
	v_lshlrev_b32_e32 v193, 2, v239
	v_mov_b32_e32 v0, 0
	v_mov_b32_e32 v1, 0
	v_mov_b32_e32 v2, 0
	v_mov_b32_e32 v3, 0
	v_mov_b32_e32 v4, 0
	v_mov_b32_e32 v5, 0
	v_mov_b32_e32 v6, 0
	v_mov_b32_e32 v7, 0
	v_mov_b32_e32 v8, 0
	v_mov_b32_e32 v9, 0
	v_mov_b32_e32 v10, 0
	v_mov_b32_e32 v11, 0
	v_mov_b32_e32 v12, 0
	v_mov_b32_e32 v13, 0
	v_mov_b32_e32 v14, 0
	v_mov_b32_e32 v15, 0
	v_mov_b32_e32 v16, 0
	v_mov_b32_e32 v17, 0
	v_mov_b32_e32 v18, 0
	v_mov_b32_e32 v19, 0
	v_mov_b32_e32 v20, 0
	v_mov_b32_e32 v21, 0
	v_mov_b32_e32 v22, 0
	v_mov_b32_e32 v23, 0
	v_mov_b32_e32 v24, 0
	v_mov_b32_e32 v25, 0
	v_mov_b32_e32 v26, 0
	v_mov_b32_e32 v27, 0
	v_mov_b32_e32 v28, 0
	v_mov_b32_e32 v29, 0
	v_mov_b32_e32 v30, 0
	v_mov_b32_e32 v31, 0
	v_mov_b32_e32 v160, 0
	v_mov_b32_e32 v161, 0
	v_mov_b32_e32 v162, 0
	v_mov_b32_e32 v163, 0
	v_mov_b32_e32 v164, 0
	v_mov_b32_e32 v165, 0
	v_mov_b32_e32 v166, 0
	v_mov_b32_e32 v167, 0
	v_mov_b32_e32 v168, 0
	v_mov_b32_e32 v169, 0
	v_mov_b32_e32 v170, 0
	v_mov_b32_e32 v171, 0
	v_mov_b32_e32 v172, 0
	v_mov_b32_e32 v173, 0
	v_mov_b32_e32 v174, 0
	v_mov_b32_e32 v175, 0
	v_mov_b32_e32 v176, 0
	v_mov_b32_e32 v177, 0
	v_mov_b32_e32 v178, 0
	v_mov_b32_e32 v179, 0
	v_mov_b32_e32 v180, 0
	v_mov_b32_e32 v181, 0
	v_mov_b32_e32 v182, 0
	v_mov_b32_e32 v183, 0
	v_mov_b32_e32 v246, 0
	v_mov_b32_e32 v247, 0
	v_mov_b32_e32 v248, 0
	v_mov_b32_e32 v249, 0
	v_mov_b32_e32 v250, 0
	v_mov_b32_e32 v251, 0
	v_mov_b32_e32 v252, 0
	v_mov_b32_e32 v253, 0
	v_readfirstlane_b32 s7, v152
	s_bfe_u32 s7, s7, 0x10006
	s_lshl_b32 s9, s38, 1
	s_add_i32 s7, s7, s9
	s_lshr_b32 s7, s7, 4
	s_cmp_eq_u32 s7, 0
	s_cbranch_scc1 .Lc0_n1
	s_cmp_eq_u32 s7, 1
	s_cbranch_scc1 .Lc0_n2
	s_cmp_eq_u32 s7, 2
	s_cbranch_scc1 .Lc0_n3
	s_branch .Lc0_n4

; #define LAS __attribute__((address_space(3)))
; __device__ __forceinline__ void phase4_attn(const Args& a, LAS unsigned char* lds) {
;     ...
;                 if (t >= 16) {
;                     __syncthreads();
;                     const int qloc = tid >> 3, jg = tid & 7;
;                     unsigned bits = 0u;
;                     float xe[4]; int cnt[4];
; #pragma unroll
;                     for (int e = 0; e < 4; ++e) { const int j = 4 * jg + e; const LAS float* ip = IMP + qloc * A_IMPSTR + j;
;                         float x = (ip[0] + ip[64 * A_IMPSTR]) + (ip[128 * A_IMPSTR] + ip[192 * A_IMPSTR]);
;                         if (j == 0 || j == t || j == t - 1) x = 1e9f;
;                         if (j > t) x = -INFINITY;
;                         xe[e] = x; cnt[e] = 0; }
; #pragma unroll 4
;                     for (int i = 0; i < 32; ++i) { const LAS float* ip = IMP + qloc * A_IMPSTR + i;
;                         float vi = (ip[0] + ip[64 * A_IMPSTR]) + (ip[128 * A_IMPSTR] + ip[192 * A_IMPSTR]);
;                         if (i == 0 || i == t || i == t - 1) vi = 1e9f;
;                         if (i > t) vi = -INFINITY;
; #pragma unroll
;                         for (int e = 0; e < 4; ++e) cnt[e] += (vi > xe[e] || (vi == xe[e] && i < 4 * jg + e)) ? 1 : 0; }
; #pragma unroll
;                     for (int e = 0; e < 4; ++e) if (cnt[e] < 16 && xe[e] > -INFINITY) bits |= 1u << (4 * jg + e);
;                     bits |= __shfl_xor(bits, 1); bits |= __shfl_xor(bits, 2); bits |= __shfl_xor(bits, 4);
;                     if (jg == 0) SELM[qloc] = bits;
;                     __syncthreads();
;                 }
;                 const unsigned selw = (t >= 16) ? SELM[ql] : ((2u << t) - 1u);
; #pragma unroll
;                 for (int ks = 0; ks < 4; ++ks) qf[ks] = __builtin_nontemporal_load((const bf16x8_t*)(qr + (size_t)tok * 512 + head * 64 + 16 * ks + 8 * h));
;                 const int kt_lo = t >= 8 ? t - 8 : 0, wlo = kt_lo >> 1, n_sel = (t >> 1) + 1, n_all = n_sel + ((t >> 1) - wlo + 1);
;                 const bf16_t* Ks = ksl + (size_t)bh * 2048 * 64; const bf16_t* Vs = vslT + (size_t)bh * 64 * 2048;
;                 const bf16_t* Kw = kwn + (size_t)bh * 2048 * 64; const bf16_t* Vw = vwnT + (size_t)bh * 64 * 2048;
.Lc0_noimp:
	s_waitcnt lgkmcnt(0)
	v_readlane_b32 s10, v254, 55
	v_readlane_b32 s11, v254, 56
	v_lshlrev_b32_e32 v200, 1, v156
	v_mov_b32_e32 v201, 0
	v_lshl_add_u64 v[202:203], s[10:11], 0, v[72:73]
	v_lshl_add_u64 v[202:203], v[202:203], 0, v[200:201]
	global_load_dwordx4 v[80:83], v[202:203], off nt
	global_load_dwordx4 v[84:87], v[202:203], off offset:32 nt
	global_load_dwordx4 v[88:91], v[202:203], off offset:64 nt
	global_load_dwordx4 v[92:95], v[202:203], off offset:96 nt
	global_load_dword v159, v[202:203], off offset:512
	v_mov_b32_e32 v200, v152
	v_lshlrev_b64 v[200:201], 4, v[200:201]
	v_lshl_add_u64 v[206:207], v[200:201], 0, s[40:41]
	v_readlane_b32 s10, v254, 41
	v_readlane_b32 s11, v254, 42
	s_nop 1
	v_lshl_add_u64 v[204:205], s[10:11], 0, v[200:201]
	global_load_dwordx4 v[208:211], v[204:205], off
	v_lshl_add_u64 v[204:205], s[10:11], 0, v[206:207]
	global_load_dwordx4 v[212:215], v[204:205], off
	v_readlane_b32 s10, v254, 33
	v_readlane_b32 s11, v254, 34
	s_nop 1
	v_lshl_add_u64 v[204:205], s[10:11], 0, v[200:201]
	global_load_dwordx4 v[104:107], v[204:205], off
	v_lshl_add_u64 v[204:205], s[10:11], 0, v[206:207]
	global_load_dwordx4 v[108:111], v[204:205], off
	s_lshl_b32 s30, 2, s38
	s_add_i32 s30, s30, -1
	s_add_i32 s80, s38, -1
	v_mov_b32_e32 v158, s30
	s_cmp_gt_u32 s38, 15
	s_cselect_b64 s[2:3], 0, -1
	s_andn2_b64 vcc, exec, s[0:1]
	s_cbranch_vccnz .LBB0_725
	s_movk_i32 s0, 0x84
	v_mul_lo_u32 v50, v99, s0
	v_readlane_b32 s0, v254, 28
	v_and_b32_e32 v33, 7, v152
	s_nop 0
	v_add_u32_e32 v46, s0, v50
	v_lshl_add_u32 v32, v33, 4, v46
	v_add_u32_e32 v40, 0x2100, v32
	v_add_u32_e32 v36, 0x4200, v32
	v_add_u32_e32 v38, 0x6300, v32
	s_barrier
	ds_read2_b32 v[34:35], v32 offset1:1
	ds_read2_b32 v[36:37], v36 offset1:1
	ds_read2_b32 v[38:39], v38 offset1:1
	ds_read2_b32 v[40:41], v40 offset1:1
	v_lshlrev_b32_e32 v32, 2, v33
	s_waitcnt lgkmcnt(3)
	v_mov_b32_e32 v42, v34
	s_waitcnt lgkmcnt(2)
	v_mov_b32_e32 v43, v36
	s_waitcnt lgkmcnt(1)
	v_mov_b32_e32 v45, v38
	s_waitcnt lgkmcnt(0)
	v_mov_b32_e32 v44, v40
	v_cmp_eq_u32_e32 vcc, 0, v33
	v_cmp_eq_u32_e64 s[0:1], s38, v32
	v_pk_add_f32 v[42:43], v[42:43], v[44:45]
	s_or_b64 s[4:5], vcc, s[0:1]
	v_cmp_eq_u32_e64 s[0:1], s80, v32
	v_add_f32_e32 v34, v42, v43
	s_or_b64 s[0:1], s[4:5], s[0:1]
	v_cndmask_b32_e64 v33, v34, v190, s[0:1]
	v_cmp_ge_u32_e64 s[0:1], s38, v32
	v_mov_b32_e32 v36, v35
	v_mov_b32_e32 v38, v41
	v_cndmask_b32_e64 v34, v191, v33, s[0:1]
	v_or_b32_e32 v33, 1, v32
	v_pk_add_f32 v[36:37], v[36:37], v[38:39]
	v_cmp_eq_u32_e64 s[0:1], s38, v33
	v_cmp_eq_u32_e64 s[4:5], s80, v33
	v_add_f32_e32 v35, v36, v37
	s_or_b64 s[0:1], s[0:1], s[4:5]
	v_or_b32_e32 v38, 2, v32
	v_cndmask_b32_e64 v33, v35, v190, s[0:1]
	v_lshl_add_u32 v35, v38, 2, v46
	v_add_u32_e32 v36, 0x2100, v35
	v_add_u32_e32 v37, 0x4200, v35
	v_add_u32_e32 v39, 0x6300, v35
	ds_read2_b32 v[40:41], v35 offset1:1
	ds_read2_b32 v[44:45], v36 offset1:1
	ds_read2_b32 v[46:47], v37 offset1:1
	ds_read2_b32 v[48:49], v39 offset1:1
	v_cmp_gt_u32_e64 s[0:1], s38, v32
	v_or_b32_e32 v42, 3, v32
	s_waitcnt lgkmcnt(2)
	v_pk_add_f32 v[40:41], v[40:41], v[44:45]
	v_cndmask_b32_e64 v36, v191, v33, s[0:1]
	s_waitcnt lgkmcnt(0)
	v_pk_add_f32 v[44:45], v[46:47], v[48:49]
	v_cmp_eq_u32_e64 s[0:1], s38, v38
	v_cmp_eq_u32_e64 s[6:7], s80, v38
	v_pk_add_f32 v[40:41], v[40:41], v[44:45]
	v_cmp_eq_u32_e64 s[4:5], s38, v42
	v_cmp_eq_u32_e64 s[8:9], s80, v42
	s_or_b64 s[0:1], s[0:1], s[6:7]
	v_cndmask_b32_e64 v37, v40, v190, s[0:1]
	s_or_b64 s[0:1], s[4:5], s[8:9]
	v_cndmask_b32_e64 v33, v41, v190, s[0:1]
	v_cmp_ge_u32_e64 s[0:1], s38, v42
	s_mov_b32 s31, 0
	s_mov_b32 s42, 1
	v_cndmask_b32_e64 v33, v191, v33, s[0:1]
	v_cmp_ge_u32_e64 s[0:1], s38, v38
	v_mov_b32_e32 v35, v32
	s_mov_b32 s43, s38
	v_cndmask_b32_e64 v40, v191, v37, s[0:1]
	s_mov_b32 s44, s80
	v_mov_b32_e32 v37, v34
	v_mov_b32_e32 v39, v36
	v_mov_b32_e32 v41, v38
	v_mov_b32_e32 v44, v40
	v_mov_b32_e32 v43, v40
	v_mov_b32_e32 v45, v42
	v_mov_b32_e32 v46, v33
	v_mov_b32_e32 v47, v33
	v_add_u32_e32 v48, 0, v50
	v_mov_b32_e32 v49, 0
	v_mov_b32_e32 v50, 0
	v_mov_b32_e32 v51, 0
	v_mov_b32_e32 v52, 0
	v_mov_b32_e32 v53, 0
	v_mov_b32_e32 v54, 0
	v_mov_b32_e32 v55, 0
	v_mov_b32_e32 v56, 0
	s_mov_b32 s45, 0
